# grid barrier: non-leader workgroups issue their acquire invalidate before the spin instead of after
# speedup vs baseline: 1.0415x; 1.0084x over previous
; __device__ __forceinline__ unsigned xb_ld(unsigned* p)              { return __hip_atomic_load(p, __ATOMIC_RELAXED, __HIP_MEMORY_SCOPE_AGENT); }
; __device__ __forceinline__ unsigned xb_add(unsigned* p, unsigned v) { return __hip_atomic_fetch_add(p, v, __ATOMIC_RELAXED, __HIP_MEMORY_SCOPE_AGENT); }
; #define XB_SPIN(cond, bar) do { unsigned _sp = 0; while (cond) { __builtin_amdgcn_s_sleep(1); \
;     if ((++_sp & 255u) == 0u) { if (xb_ld(&(bar)[XB_TMO])) break; if (_sp > XB_SPIN_CAP) { atomicAdd(&(bar)[XB_TMO], 1u); break; } } } } while (0)
; __device__ __forceinline__ void xcd_barrier(const XcdBarrier& b) {
;     ...
;         const unsigned old = xb_add(&bar[XB_XSUB(b.x)], 1u);
;         const unsigned gen = old / nloc;
;         if (old + 1u == (gen + 1u) * nloc) {
;             __builtin_amdgcn_fence(__ATOMIC_RELEASE, "agent");
;             asm volatile("s_waitcnt vmcnt(0)" ::: "memory");
;             const unsigned og = xb_add(&bar[XB_TOP], 1u);
;             const unsigned tg = og / nx;
;             if (og + 1u == (tg + 1u) * nx) xb_add(&bar[XB_TOPGEN], 1u);
;             else XB_SPIN(xb_ld(&bar[XB_TOPGEN]) == tg, bar);
;             __builtin_amdgcn_fence(__ATOMIC_ACQUIRE, "agent");
;             xb_add(&bar[XB_XGEN(b.x)], 1u);
;             asm volatile("s_waitcnt vmcnt(0)" ::: "memory");
;         } else {
;             XB_SPIN(xb_ld(&bar[XB_XGEN(b.x)]) == gen, bar);
;             __builtin_amdgcn_fence(__ATOMIC_ACQUIRE, "agent");
;             asm volatile("s_waitcnt vmcnt(0)" ::: "memory");
.LBB0_194:
	s_or_b64 exec, exec, s[8:9]
	v_cvt_f32_u32_e32 v10, v8
	s_waitcnt vmcnt(0)
	v_readfirstlane_b32 s6, v9
	v_sub_u32_e32 v9, 0, v8
	v_rcp_iflag_f32_e32 v10, v10
	v_add_u32_e32 v11, s6, v7
	v_mul_f32_e32 v10, 0x4f7ffffe, v10
	v_cvt_u32_f32_e32 v10, v10
	v_mul_lo_u32 v7, v9, v10
	v_mul_hi_u32 v7, v10, v7
	v_add_u32_e32 v7, v10, v7
	v_mul_hi_u32 v7, v11, v7
	v_mul_lo_u32 v9, v7, v8
	v_sub_u32_e32 v9, v11, v9
	v_add_u32_e32 v10, 1, v7
	v_cmp_ge_u32_e32 vcc, v9, v8
	s_nop 1
	v_cndmask_b32_e32 v7, v7, v10, vcc
	v_sub_u32_e32 v10, v9, v8
	v_cndmask_b32_e32 v9, v9, v10, vcc
	v_add_u32_e32 v10, 1, v7
	v_cmp_ge_u32_e32 vcc, v9, v8
	v_add_u32_e32 v9, 1, v11
	s_nop 0
	v_cndmask_b32_e32 v7, v7, v10, vcc
	v_mul_lo_u32 v10, v8, v7
	v_add_u32_e32 v8, v10, v8
	v_cmp_ne_u32_e32 vcc, v9, v8
	s_and_saveexec_b64 s[6:7], vcc
	s_xor_b64 s[6:7], exec, s[6:7]
	s_cbranch_execz .LBB0_208
	s_waitcnt lgkmcnt(0)
	buffer_inv sc1
	v_mov_b32_e32 v6, 0x2000
	global_load_dword v6, v6, s[4:5] offset:1024 sc1
	s_add_u32 s10, s4, 0x2400
	s_addc_u32 s11, s5, 0
	s_waitcnt vmcnt(0)
	v_cmp_eq_u32_e32 vcc, v6, v7
	s_and_saveexec_b64 s[8:9], vcc
	s_cbranch_execz .LBB0_207
	s_mov_b32 s16, 1
	s_mov_b64 s[12:13], 0
	s_branch .LBB0_198

; __device__ __forceinline__ unsigned xb_ld(unsigned* p)              { return __hip_atomic_load(p, __ATOMIC_RELAXED, __HIP_MEMORY_SCOPE_AGENT); }
; #define XB_SPIN(cond, bar) do { unsigned _sp = 0; while (cond) { __builtin_amdgcn_s_sleep(1); \
;     if ((++_sp & 255u) == 0u) { if (xb_ld(&(bar)[XB_TMO])) break; if (_sp > XB_SPIN_CAP) { atomicAdd(&(bar)[XB_TMO], 1u); break; } } } } while (0)
; __device__ __forceinline__ void xcd_barrier(const XcdBarrier& b) {
;     ...
;             XB_SPIN(xb_ld(&bar[XB_XGEN(b.x)]) == gen, bar);
;             __builtin_amdgcn_fence(__ATOMIC_ACQUIRE, "agent");
;             asm volatile("s_waitcnt vmcnt(0)" ::: "memory");
.LBB0_207:
	s_or_b64 exec, exec, s[8:9]
	s_waitcnt vmcnt(0)
	s_waitcnt vmcnt(0)
